# combo (fastdiv, dilcomb, cmp, gemmA/B dma, qk, nsamask) bal1 bswap4
# speedup vs baseline: 1.0025x; 1.0025x over previous
; __global__ void __launch_bounds__(256, 2) hybrid_megakernel(Params p) {
;     ...
;       const int gi = vb >> 4;
;       int start = 0, mine = 0;
;       for (int g2 = 0; g2 <= gi; ++g2) {
;         const int n = 32 - g2;
;         const int d = (n <= 10) ? 2 : (n <= 22) ? 1 : 0;
;         if (g2 < gi) start += 2 * d; else mine = d;
;       }
;       start += ((vb >> 3) & 1) * mine;
.LBB0_407:
	s_cmp_ge_u32 s2, 1
	s_cselect_b64 s[4:5], -1, 0
	s_cmp_lt_u32 s2, 31
	v_cndmask_b32_e64 v1, 0, 1, s[4:5]
	s_cselect_b64 vcc, -1, 0
	v_cndmask_b32_e32 v1, 2, v1, vcc
	s_cmp_lt_i32 s2, s0
	v_lshlrev_b32_e32 v2, 1, v1
	s_cselect_b64 vcc, -1, 0
	s_add_i32 s2, s2, 1
	v_cndmask_b32_e32 v2, 0, v2, vcc
	v_cndmask_b32_e32 v116, v1, v116, vcc
	s_cmp_eq_u32 s1, s2
	v_add_u32_e32 v0, v2, v0
	s_cbranch_scc0 .LBB0_407
	v_cmp_gt_i32_e32 vcc, 1, v116
	s_cbranch_vccz .LBB0_410
	s_branch .LBB0_345
